# the 27 per-unit SMEM loads of gridDim.x (unit headers of every phase) replaced by the constant 256 the host always launches
# speedup vs baseline: 1.0144x; 1.0040x over previous
.LBB0_88:
	v_readlane_b32 s0, v251, 36
	s_nop 1
	v_lshl_add_u32 v0, s0, 6, v64
	s_mov_b32 s0, s91
	s_cmp_lt_i32 s0, 0
	s_cbranch_scc1 .LBB0_156
	v_mbcnt_lo_u32_b32 v220, -1, 0
	v_mbcnt_hi_u32_b32 v220, -1, v220
	s_movk_i32 s1, 0x100
	s_add_u32 s2, s62, 0x1bee0000
	s_addc_u32 s3, s63, 0
	v_writelane_b32 v251, s2, 41
	v_writelane_b32 v251, s3, 42
	v_writelane_b32 v252, s56, 26
	v_writelane_b32 v252, s57, 27
	v_readlane_b32 s4, v251, 36
	s_lshl_b32 s0, s91, 3
	s_nop 0
	s_add_i32 s0, s0, s4
	s_mul_i32 s15, s4, 0x2100
	s_movk_i32 s14, 0x3800
	s_mov_b32 s12, 0
	s_waitcnt lgkmcnt(0)
	s_lshl_b32 s1, s1, 3
	s_cmp_lg_u32 s1, 0x800
	s_cbranch_scc1 .Lcvth_nobal
	s_cmp_gt_u32 s91, 63
	s_cbranch_scc1 .Lcvth_clsb
	s_movk_i32 s1, 0x200
	s_movk_i32 s14, 0x800
	s_branch .Lcvth_nobal

.LBB0_165:
	s_waitcnt lgkmcnt(0)
	global_load_dword v15, v33, s[56:57] sc1
	global_load_dword v14, v33, s[58:59] sc1
	global_load_dword v13, v33, s[60:61] sc1
	v_readlane_b32 s0, v251, 45
	v_readlane_b32 s1, v251, 46
	s_nop 4
	global_load_dword v12, v33, s[0:1] sc1
	v_readlane_b32 s0, v251, 47
	v_readlane_b32 s1, v251, 48
	s_nop 4
	global_load_dword v11, v33, s[0:1] sc1
	v_readlane_b32 s0, v251, 49
	v_readlane_b32 s1, v251, 50
	s_nop 4
	global_load_dword v10, v33, s[0:1] sc1
	v_readlane_b32 s0, v251, 51
	v_readlane_b32 s1, v251, 52
	s_nop 4
	global_load_dword v9, v33, s[0:1] sc1
	v_readlane_b32 s0, v251, 53
	v_readlane_b32 s1, v251, 54
	s_nop 4
	global_load_dword v8, v33, s[0:1] sc1
	v_readlane_b32 s0, v251, 55
	v_readlane_b32 s1, v251, 56
	s_nop 4
	global_load_dword v7, v33, s[0:1] sc1
	v_readlane_b32 s0, v251, 57
	v_readlane_b32 s1, v251, 58
	s_nop 4
	global_load_dword v6, v33, s[0:1] sc1
	v_readlane_b32 s0, v251, 59
	v_readlane_b32 s1, v251, 60
	s_nop 4
	global_load_dword v5, v33, s[0:1] sc1
	v_readlane_b32 s0, v251, 61
	v_readlane_b32 s1, v251, 62
	s_nop 4
	global_load_dword v4, v33, s[0:1] sc1
	v_readlane_b32 s0, v251, 63
	v_readlane_b32 s1, v252, 0
	s_nop 4
	global_load_dword v3, v33, s[0:1] sc1
	v_readlane_b32 s0, v252, 1
	v_readlane_b32 s1, v252, 2
	s_nop 4
	global_load_dword v2, v33, s[0:1] sc1
	v_readlane_b32 s0, v252, 3
	v_readlane_b32 s1, v252, 4
	s_nop 4
	global_load_dword v1, v33, s[0:1] sc1
	v_readlane_b32 s0, v252, 5
	v_readlane_b32 s1, v252, 6
	s_nop 4
	global_load_dword v0, v33, s[0:1] sc1
	s_movk_i32 s2, 0x100
	s_waitcnt vmcnt(0)
	v_readfirstlane_b32 s86, v15
	v_add_u32_e32 v15, v14, v15
	v_add_u32_e32 v15, v15, v13
	v_add_u32_e32 v15, v15, v12
	v_add_u32_e32 v15, v15, v11
	v_add_u32_e32 v15, v15, v10
	v_add_u32_e32 v15, v15, v9
	v_add_u32_e32 v15, v15, v8
	v_add_u32_e32 v15, v15, v7
	v_add_u32_e32 v15, v15, v6
	v_add_u32_e32 v15, v15, v5
	v_add_u32_e32 v15, v15, v4
	v_add_u32_e32 v15, v15, v3
	v_add_u32_e32 v15, v15, v2
	v_add_u32_e32 v15, v15, v1
	v_add_u32_e32 v15, v15, v0
	s_mov_b64 s[0:1], -1
	s_waitcnt lgkmcnt(0)
	v_cmp_eq_u32_e32 vcc, s2, v15
	s_mov_b64 s[2:3], -1
	s_cbranch_vccnz .LBB0_164
	s_and_b32 s0, s6, 0xff
	s_cmp_eq_u32 s0, 0
	s_mov_b64 s[0:1], -1
	s_mov_b64 s[4:5], -1
	s_sleep 1
	s_cbranch_scc1 .LBB0_169
	s_and_b64 vcc, exec, s[4:5]
	s_cbranch_vccz .LBB0_164

.LBB0_218:
	s_or_b64 exec, exec, s[6:7]
	s_movk_i32 s6, 0x4100
	v_cmp_gt_i32_e32 vcc, s6, v58
	s_and_saveexec_b64 s[6:7], vcc
	s_cbranch_execz .LBB0_243
	s_waitcnt vmcnt(3)
	v_pk_add_f32 v[4:5], v[4:5], 1.0 op_sel_hi:[1,0]
	v_mov_b32_e32 v75, v33
	v_pk_mul_f32 v[94:95], v[0:1], v[4:5]
	v_and_b32_e32 v0, 64, v220
	v_add_u32_e32 v0, 64, v0
	v_xor_b32_e32 v1, 1, v220
	v_cmp_lt_i32_e32 vcc, v1, v0
	v_lshl_add_u64 v[78:79], s[8:9], 0, v[74:75]
	s_and_b64 s[8:9], s[2:3], exec
	v_cndmask_b32_e32 v1, v220, v1, vcc
	v_lshlrev_b32_e32 v116, 2, v1
	v_xor_b32_e32 v1, 2, v220
	v_cmp_lt_i32_e32 vcc, v1, v0
	s_movk_i32 s8, 0x100
	s_cselect_b32 s23, 0, 11
	v_cndmask_b32_e32 v1, v220, v1, vcc
	v_lshlrev_b32_e32 v117, 2, v1
	v_xor_b32_e32 v1, 4, v220
	v_cmp_lt_i32_e32 vcc, v1, v0
	s_waitcnt lgkmcnt(0)
	s_lshl_b32 s8, s8, 3
	s_add_u32 s12, s0, 0x9000
	v_cndmask_b32_e32 v1, v220, v1, vcc
	v_lshlrev_b32_e32 v118, 2, v1
	v_xor_b32_e32 v1, 8, v220
	v_cmp_lt_i32_e32 vcc, v1, v0
	s_addc_u32 s13, s1, 0
	s_ashr_i32 s9, s8, 31
	v_cndmask_b32_e32 v1, v220, v1, vcc
	v_lshlrev_b32_e32 v119, 2, v1
	v_xor_b32_e32 v1, 16, v220
	v_cmp_lt_i32_e32 vcc, v1, v0
	s_lshl_b64 s[10:11], s[8:9], 11
	s_add_i32 s24, s23, -1
	v_cndmask_b32_e32 v1, v220, v1, vcc
	v_lshlrev_b32_e32 v120, 2, v1
	v_xor_b32_e32 v1, 32, v220
	v_cmp_lt_i32_e32 vcc, v1, v0
	s_add_u32 s0, s0, 0xa000
	v_pk_add_f32 v[6:7], v[6:7], 1.0 op_sel_hi:[1,0]
	v_cndmask_b32_e32 v0, v220, v1, vcc
	s_addc_u32 s1, s1, 0
	v_pk_add_f32 v[38:39], v[38:39], 1.0 op_sel_hi:[1,0]
	v_pk_add_f32 v[40:41], v[40:41], 1.0 op_sel_hi:[1,0]
	v_pk_mul_f32 v[92:93], v[2:3], v[6:7]
	v_lshlrev_b32_e32 v121, 2, v0
	v_readlane_b32 s14, v252, 9
	v_lshl_add_u64 v[98:99], s[0:1], 0, v[74:75]
	v_lshl_add_u64 v[102:103], s[0:1], 0, v[32:33]
	v_lshlrev_b64 v[0:1], 12, v[58:59]
	v_and_b32_e32 v2, 63, v60
	v_readlane_b32 s0, v252, 11
	v_pk_add_f32 v[56:57], v[56:57], 1.0 op_sel_hi:[1,0]
	v_pk_add_f32 v[54:55], v[54:55], 1.0 op_sel_hi:[1,0]
	v_pk_mul_f32 v[84:85], v[14:15], v[40:41]
	v_pk_mul_f32 v[86:87], v[12:13], v[38:39]
	s_waitcnt vmcnt(2)
	v_pk_add_f32 v[12:13], v[36:37], 1.0 op_sel_hi:[1,0]
	v_pk_add_f32 v[14:15], v[34:35], 1.0 op_sel_hi:[1,0]
	v_mov_b32_e32 v77, v33
	v_readlane_b32 s15, v252, 10
	v_lshl_or_b32 v0, v2, 5, v0
	v_readlane_b32 s1, v252, 12
	v_pk_mul_f32 v[80:81], v[52:53], v[56:57]
	v_pk_mul_f32 v[82:83], v[50:51], v[54:55]
	v_pk_mul_f32 v[88:89], v[10:11], v[12:13]
	v_pk_mul_f32 v[90:91], v[8:9], v[14:15]
	v_lshl_add_u64 v[96:97], s[14:15], 0, v[76:77]
	v_lshl_add_u64 v[100:101], s[12:13], 0, v[74:75]
	v_lshl_add_u64 v[104:105], s[12:13], 0, v[32:33]
	v_lshl_add_u64 v[106:107], s[0:1], 0, v[0:1]
	s_lshl_b64 s[12:13], s[8:9], 12
	s_mov_b64 s[14:15], 0
	s_branch .LBB0_221

.LBB0_254:
	v_readlane_b32 s0, v251, 45
	v_readlane_b32 s1, v251, 46
	global_load_dword v15, v33, s[56:57] sc1
	global_load_dword v14, v33, s[58:59] sc1
	global_load_dword v13, v33, s[60:61] sc1
	s_waitcnt vmcnt(2)
	v_readfirstlane_b32 s79, v15
	global_load_dword v12, v33, s[0:1] sc1
	v_readlane_b32 s0, v251, 47
	v_readlane_b32 s1, v251, 48
	s_waitcnt vmcnt(2)
	v_add_u32_e32 v15, v14, v15
	s_waitcnt vmcnt(1)
	v_add_u32_e32 v15, v15, v13
	s_waitcnt vmcnt(0)
	v_add_u32_e32 v15, v15, v12
	global_load_dword v11, v33, s[0:1] sc1
	v_readlane_b32 s0, v251, 49
	v_readlane_b32 s1, v251, 50
	s_waitcnt vmcnt(0)
	v_add_u32_e32 v15, v15, v11
	s_nop 2
	global_load_dword v10, v33, s[0:1] sc1
	v_readlane_b32 s0, v251, 51
	v_readlane_b32 s1, v251, 52
	s_waitcnt vmcnt(0)
	v_add_u32_e32 v15, v15, v10
	s_nop 2
	global_load_dword v9, v33, s[0:1] sc1
	v_readlane_b32 s0, v251, 53
	v_readlane_b32 s1, v251, 54
	s_waitcnt vmcnt(0)
	v_add_u32_e32 v15, v15, v9
	s_nop 2
	global_load_dword v8, v33, s[0:1] sc1
	v_readlane_b32 s0, v251, 55
	v_readlane_b32 s1, v251, 56
	s_waitcnt vmcnt(0)
	v_add_u32_e32 v15, v15, v8
	s_nop 2
	global_load_dword v7, v33, s[0:1] sc1
	v_readlane_b32 s0, v251, 57
	v_readlane_b32 s1, v251, 58
	s_waitcnt vmcnt(0)
	v_add_u32_e32 v15, v15, v7
	s_nop 2
	global_load_dword v6, v33, s[0:1] sc1
	v_readlane_b32 s0, v251, 59
	v_readlane_b32 s1, v251, 60
	s_waitcnt vmcnt(0)
	v_add_u32_e32 v15, v15, v6
	s_nop 2
	global_load_dword v5, v33, s[0:1] sc1
	v_readlane_b32 s0, v251, 61
	v_readlane_b32 s1, v251, 62
	s_waitcnt vmcnt(0)
	v_add_u32_e32 v15, v15, v5
	s_nop 2
	global_load_dword v4, v33, s[0:1] sc1
	v_readlane_b32 s0, v251, 63
	v_readlane_b32 s1, v252, 0
	s_waitcnt vmcnt(0)
	v_add_u32_e32 v15, v15, v4
	s_nop 2
	global_load_dword v3, v33, s[0:1] sc1
	v_readlane_b32 s0, v252, 1
	v_readlane_b32 s1, v252, 2
	s_waitcnt vmcnt(0)
	v_add_u32_e32 v15, v15, v3
	s_nop 2
	global_load_dword v2, v33, s[0:1] sc1
	v_readlane_b32 s0, v252, 3
	v_readlane_b32 s1, v252, 4
	s_waitcnt vmcnt(0)
	v_add_u32_e32 v15, v15, v2
	s_nop 2
	global_load_dword v1, v33, s[0:1] sc1
	v_readlane_b32 s0, v252, 5
	v_readlane_b32 s1, v252, 6
	s_waitcnt vmcnt(0)
	v_add_u32_e32 v15, v15, v1
	s_waitcnt lgkmcnt(0)
	s_nop 1
	global_load_dword v0, v33, s[0:1] sc1
	s_movk_i32 s2, 0x100
	s_mov_b64 s[0:1], -1
	s_waitcnt vmcnt(0)
	v_add_u32_e32 v15, v15, v0
	s_waitcnt lgkmcnt(0)
	v_cmp_eq_u32_e32 vcc, s2, v15
	s_mov_b64 s[2:3], -1
	s_cbranch_vccnz .LBB0_253
	s_and_b32 s0, s6, 0xff
	s_cmp_eq_u32 s0, 0
	s_mov_b64 s[0:1], -1
	s_mov_b64 s[4:5], -1
	s_sleep 1
	s_cbranch_scc1 .LBB0_258
	s_and_b64 vcc, exec, s[4:5]
	s_cbranch_vccz .LBB0_253

.LBB0_307:
	s_or_b64 exec, exec, s[0:1]
	s_movk_i32 s0, 0x4100
	v_cmp_gt_i32_e32 vcc, s0, v58
	s_and_saveexec_b64 s[4:5], vcc
	s_cbranch_execz .LBB0_318
	s_waitcnt vmcnt(0)
	v_pk_add_f32 v[46:47], v[46:47], 1.0 op_sel_hi:[1,0]
	v_readlane_b32 s0, v252, 54
	v_pk_mul_f32 v[84:85], v[20:21], v[46:47]
	s_waitcnt vmcnt(2)
	v_pk_add_f32 v[20:21], v[44:45], 1.0 op_sel_hi:[1,0]
	v_mov_b32_e32 v61, v33
	v_pk_mul_f32 v[86:87], v[40:41], v[20:21]
	v_pk_add_f32 v[20:21], v[34:35], 1.0 op_sel_hi:[1,0]
	v_readlane_b32 s1, v252, 55
	v_pk_mul_f32 v[92:93], v[16:17], v[20:21]
	v_and_b32_e32 v16, 64, v220
	v_add_u32_e32 v16, 64, v16
	v_xor_b32_e32 v17, 1, v220
	v_cmp_lt_i32_e32 vcc, v17, v16
	v_mov_b32_e32 v63, v33
	v_lshl_add_u64 v[74:75], s[0:1], 0, v[60:61]
	v_cndmask_b32_e32 v17, v220, v17, vcc
	v_lshlrev_b32_e32 v32, 2, v17
	v_xor_b32_e32 v17, 2, v220
	v_cmp_lt_i32_e32 vcc, v17, v16
	v_lshl_add_u64 v[76:77], s[0:1], 0, v[62:63]
	s_movk_i32 s0, 0x100
	v_cndmask_b32_e32 v17, v220, v17, vcc
	v_lshlrev_b32_e32 v124, 2, v17
	v_xor_b32_e32 v17, 4, v220
	v_cmp_lt_i32_e32 vcc, v17, v16
	v_pk_add_f32 v[48:49], v[48:49], 1.0 op_sel_hi:[1,0]
	s_waitcnt lgkmcnt(0)
	s_lshl_b32 s6, s0, 3
	v_cndmask_b32_e32 v17, v220, v17, vcc
	v_lshlrev_b32_e32 v125, 2, v17
	v_xor_b32_e32 v17, 8, v220
	v_cmp_lt_i32_e32 vcc, v17, v16
	v_pk_mul_f32 v[82:83], v[22:23], v[48:49]
	v_pk_add_f32 v[22:23], v[42:43], 1.0 op_sel_hi:[1,0]
	v_cndmask_b32_e32 v17, v220, v17, vcc
	v_lshlrev_b32_e32 v126, 2, v17
	v_xor_b32_e32 v17, 16, v220
	v_cmp_lt_i32_e32 vcc, v17, v16
	s_ashr_i32 s7, s6, 31
	v_lshlrev_b64 v[102:103], 11, v[58:59]
	v_cndmask_b32_e32 v17, v220, v17, vcc
	v_lshlrev_b32_e32 v127, 2, v17
	v_xor_b32_e32 v17, 32, v220
	v_cmp_lt_i32_e32 vcc, v17, v16
	v_pk_mul_f32 v[88:89], v[38:39], v[22:23]
	v_pk_add_f32 v[22:23], v[36:37], 1.0 op_sel_hi:[1,0]
	v_cndmask_b32_e32 v16, v220, v17, vcc
	v_lshlrev_b32_e32 v128, 2, v16
	v_and_b32_e32 v16, 63, v64
	s_lshl_b64 s[8:9], s[6:7], 11
	v_readlane_b32 s2, v252, 62
	v_readlane_b32 s0, v252, 60
	v_lshl_or_b32 v102, v16, 4, v102
	v_lshlrev_b64 v[106:107], 12, v[58:59]
	v_pk_add_f32 v[56:57], v[56:57], 1.0 op_sel_hi:[1,0]
	v_pk_add_f32 v[54:55], v[54:55], 1.0 op_sel_hi:[1,0]
	v_pk_mul_f32 v[90:91], v[18:19], v[22:23]
	v_readlane_b32 s3, v252, 63
	v_readlane_b32 s1, v252, 61
	v_lshl_add_u64 v[104:105], v[102:103], 0, s[8:9]
	v_lshl_or_b32 v106, v16, 5, v106
	s_waitcnt vmcnt(1)
	v_mov_b64_e32 v[16:17], v[28:29]
	s_waitcnt vmcnt(0)
	v_mov_b64_e32 v[20:21], v[24:25]
	v_pk_mul_f32 v[78:79], v[52:53], v[56:57]
	v_pk_mul_f32 v[80:81], v[50:51], v[54:55]
	v_lshl_add_u64 v[94:95], s[2:3], 0, v[60:61]
	v_lshl_add_u64 v[96:97], s[0:1], 0, v[60:61]
	v_lshl_add_u64 v[98:99], s[2:3], 0, v[62:63]
	v_lshl_add_u64 v[100:101], s[0:1], 0, v[62:63]
	v_or_b32_e32 v104, 0x400, v104
	s_lshl_b64 s[10:11], s[6:7], 12
	s_mov_b64 s[12:13], 0
	v_mov_b64_e32 v[18:19], v[30:31]
	v_mov_b64_e32 v[22:23], v[26:27]
	s_branch .LBB0_310

.LBB0_392:
	s_movk_i32 s7, 0x100
	s_add_i32 s31, s31, 1
	s_mov_b64 s[4:5], s[8:9]
	s_mov_b64 s[14:15], s[10:11]
	s_mov_b32 s34, s6
	s_waitcnt lgkmcnt(0)
	s_mul_i32 s7, s31, s7
	s_add_i32 s7, s7, s20
	s_cmpk_gt_i32 s7, 0x8a1
	s_cselect_b64 s[12:13], -1, 0
	s_mov_b32 s35, s21
	s_and_b64 vcc, exec, s[12:13]
	s_cbranch_vccnz .LBB0_402
	s_ashr_i32 s6, s7, 31
	s_lshr_b32 s6, s6, 29
	s_add_i32 s8, s7, s6
	s_and_b32 s6, s8, -8
	s_sub_i32 s9, s7, s6
	s_cmp_gt_i32 s9, 1
	s_mov_b64 s[6:7], -1
	s_cbranch_scc0 .LBB0_395
	s_mul_i32 s6, s9, 0x114
	s_or_b32 s10, s6, 2
	s_mov_b64 s[6:7], 0

.LBB0_517:
	s_or_b64 exec, exec, s[2:3]
	s_waitcnt vmcnt(0)
	ds_write_b128 v110, v[0:3]
	ds_write_b128 v111, v[4:7]
	ds_write_b128 v112, v[8:11]
	ds_write_b128 v113, v[12:15]
	ds_write_b128 v114, v[16:19]
	ds_write_b128 v115, v[20:23]
	ds_write_b128 v116, v[24:27]
	ds_write_b128 v117, v[28:31]
	s_waitcnt lgkmcnt(0)
	s_barrier
	ds_read_b128 v[50:53], v118 offset:512
	v_cvt_f32_f16_sdwa v63, v34 dst_sel:DWORD dst_unused:UNUSED_PAD src0_sel:WORD_1
	v_cvt_f32_f16_e32 v62, v34
	ds_read_b128 v[54:57], v118
	ds_read_b128 v[58:61], v118 offset:16
	s_waitcnt lgkmcnt(2)
	v_pk_mul_f32 v[50:51], v[50:51], v[62:63]
	s_waitcnt lgkmcnt(1)
	v_pk_mul_f32 v[54:55], v[54:55], v[62:63]
	v_cvt_f32_f16_sdwa v63, v35 dst_sel:DWORD dst_unused:UNUSED_PAD src0_sel:WORD_1
	v_cvt_f32_f16_e32 v62, v35
	v_cvt_pk_f16_f32 v50, v50, v51
	v_cvt_pk_f16_f32 v54, v54, v55
	v_pk_mul_f32 v[52:53], v[52:53], v[62:63]
	s_nop 0
	v_cvt_pk_f16_f32 v51, v52, v53
	v_pk_mul_f32 v[52:53], v[56:57], v[62:63]
	ds_read_b128 v[62:65], v118 offset:528
	v_cvt_f32_f16_sdwa v57, v36 dst_sel:DWORD dst_unused:UNUSED_PAD src0_sel:WORD_1
	v_cvt_f32_f16_e32 v56, v36
	v_cvt_pk_f16_f32 v55, v52, v53
	s_waitcnt lgkmcnt(0)
	v_pk_mul_f32 v[52:53], v[62:63], v[56:57]
	v_pk_mul_f32 v[56:57], v[58:59], v[56:57]
	v_cvt_f32_f16_sdwa v59, v37 dst_sel:DWORD dst_unused:UNUSED_PAD src0_sel:WORD_1
	v_cvt_f32_f16_e32 v58, v37
	v_cvt_pk_f16_f32 v56, v56, v57
	v_cvt_pk_f16_f32 v52, v52, v53
	v_pk_mul_f32 v[62:63], v[64:65], v[58:59]
	v_pk_mul_f32 v[58:59], v[60:61], v[58:59]
	v_cvt_pk_f16_f32 v53, v62, v63
	v_cvt_pk_f16_f32 v57, v58, v59
	ds_write_b128 v101, v[54:57]
	ds_write_b128 v102, v[50:53]
	ds_read_b128 v[50:53], v118 offset:512
	v_cvt_f32_f16_sdwa v63, v38 dst_sel:DWORD dst_unused:UNUSED_PAD src0_sel:WORD_1
	v_cvt_f32_f16_e32 v62, v38
	ds_read_b128 v[54:57], v118
	ds_read_b128 v[58:61], v118 offset:16
	s_waitcnt lgkmcnt(2)
	v_pk_mul_f32 v[50:51], v[50:51], v[62:63]
	s_waitcnt lgkmcnt(1)
	v_pk_mul_f32 v[54:55], v[54:55], v[62:63]
	v_cvt_f32_f16_sdwa v63, v39 dst_sel:DWORD dst_unused:UNUSED_PAD src0_sel:WORD_1
	v_cvt_f32_f16_e32 v62, v39
	v_cvt_pk_f16_f32 v50, v50, v51
	v_cvt_pk_f16_f32 v54, v54, v55
	v_pk_mul_f32 v[52:53], v[52:53], v[62:63]
	s_nop 0
	v_cvt_pk_f16_f32 v51, v52, v53
	v_pk_mul_f32 v[52:53], v[56:57], v[62:63]
	ds_read_b128 v[62:65], v118 offset:528
	v_cvt_f32_f16_sdwa v57, v40 dst_sel:DWORD dst_unused:UNUSED_PAD src0_sel:WORD_1
	v_cvt_f32_f16_e32 v56, v40
	v_cvt_pk_f16_f32 v55, v52, v53
	s_waitcnt lgkmcnt(0)
	v_pk_mul_f32 v[52:53], v[62:63], v[56:57]
	v_pk_mul_f32 v[56:57], v[58:59], v[56:57]
	v_cvt_f32_f16_sdwa v59, v41 dst_sel:DWORD dst_unused:UNUSED_PAD src0_sel:WORD_1
	v_cvt_f32_f16_e32 v58, v41
	v_cvt_pk_f16_f32 v56, v56, v57
	v_cvt_pk_f16_f32 v52, v52, v53
	v_pk_mul_f32 v[62:63], v[64:65], v[58:59]
	v_pk_mul_f32 v[58:59], v[60:61], v[58:59]
	v_cvt_pk_f16_f32 v53, v62, v63
	v_cvt_pk_f16_f32 v57, v58, v59
	ds_write_b128 v103, v[54:57]
	ds_write_b128 v104, v[50:53]
	ds_read_b128 v[50:53], v118 offset:512
	v_cvt_f32_f16_sdwa v63, v42 dst_sel:DWORD dst_unused:UNUSED_PAD src0_sel:WORD_1
	v_cvt_f32_f16_e32 v62, v42
	ds_read_b128 v[54:57], v118
	ds_read_b128 v[58:61], v118 offset:16
	s_waitcnt lgkmcnt(2)
	v_pk_mul_f32 v[50:51], v[50:51], v[62:63]
	s_waitcnt lgkmcnt(1)
	v_pk_mul_f32 v[54:55], v[54:55], v[62:63]
	v_cvt_f32_f16_sdwa v63, v43 dst_sel:DWORD dst_unused:UNUSED_PAD src0_sel:WORD_1
	v_cvt_f32_f16_e32 v62, v43
	v_cvt_pk_f16_f32 v50, v50, v51
	v_cvt_pk_f16_f32 v54, v54, v55
	v_pk_mul_f32 v[52:53], v[52:53], v[62:63]
	s_nop 0
	v_cvt_pk_f16_f32 v51, v52, v53
	v_pk_mul_f32 v[52:53], v[56:57], v[62:63]
	ds_read_b128 v[62:65], v118 offset:528
	v_cvt_f32_f16_sdwa v57, v44 dst_sel:DWORD dst_unused:UNUSED_PAD src0_sel:WORD_1
	v_cvt_f32_f16_e32 v56, v44
	v_cvt_pk_f16_f32 v55, v52, v53
	s_waitcnt lgkmcnt(0)
	v_pk_mul_f32 v[52:53], v[62:63], v[56:57]
	v_pk_mul_f32 v[56:57], v[58:59], v[56:57]
	v_cvt_f32_f16_sdwa v59, v45 dst_sel:DWORD dst_unused:UNUSED_PAD src0_sel:WORD_1
	v_cvt_f32_f16_e32 v58, v45
	v_cvt_pk_f16_f32 v56, v56, v57
	v_cvt_pk_f16_f32 v52, v52, v53
	v_pk_mul_f32 v[62:63], v[64:65], v[58:59]
	v_pk_mul_f32 v[58:59], v[60:61], v[58:59]
	v_cvt_pk_f16_f32 v53, v62, v63
	v_cvt_pk_f16_f32 v57, v58, v59
	ds_write_b128 v105, v[54:57]
	ds_write_b128 v106, v[50:53]
	ds_read_b128 v[50:53], v118 offset:512
	v_cvt_f32_f16_sdwa v63, v46 dst_sel:DWORD dst_unused:UNUSED_PAD src0_sel:WORD_1
	v_cvt_f32_f16_e32 v62, v46
	ds_read_b128 v[54:57], v118
	ds_read_b128 v[58:61], v118 offset:16
	s_waitcnt lgkmcnt(2)
	v_pk_mul_f32 v[50:51], v[50:51], v[62:63]
	s_waitcnt lgkmcnt(1)
	v_pk_mul_f32 v[54:55], v[54:55], v[62:63]
	v_cvt_f32_f16_sdwa v63, v47 dst_sel:DWORD dst_unused:UNUSED_PAD src0_sel:WORD_1
	v_cvt_f32_f16_e32 v62, v47
	v_cvt_pk_f16_f32 v50, v50, v51
	v_cvt_pk_f16_f32 v54, v54, v55
	v_pk_mul_f32 v[52:53], v[52:53], v[62:63]
	s_nop 0
	v_cvt_pk_f16_f32 v51, v52, v53
	v_pk_mul_f32 v[52:53], v[56:57], v[62:63]
	ds_read_b128 v[62:65], v118 offset:528
	v_cvt_f32_f16_sdwa v57, v48 dst_sel:DWORD dst_unused:UNUSED_PAD src0_sel:WORD_1
	v_cvt_f32_f16_e32 v56, v48
	v_cvt_pk_f16_f32 v55, v52, v53
	s_waitcnt lgkmcnt(0)
	v_pk_mul_f32 v[52:53], v[62:63], v[56:57]
	v_pk_mul_f32 v[56:57], v[58:59], v[56:57]
	v_cvt_f32_f16_sdwa v59, v49 dst_sel:DWORD dst_unused:UNUSED_PAD src0_sel:WORD_1
	v_cvt_f32_f16_e32 v58, v49
	v_cvt_pk_f16_f32 v56, v56, v57
	v_cvt_pk_f16_f32 v52, v52, v53
	v_pk_mul_f32 v[62:63], v[64:65], v[58:59]
	v_pk_mul_f32 v[58:59], v[60:61], v[58:59]
	v_cvt_pk_f16_f32 v53, v62, v63
	v_cvt_pk_f16_f32 v57, v58, v59
	ds_write_b128 v107, v[54:57]
	ds_write_b128 v108, v[50:53]
	s_waitcnt lgkmcnt(0)
	s_barrier
	s_movk_i32 s2, 0x100
	s_waitcnt lgkmcnt(0)
	s_add_i32 s6, s8, s2
	s_cmpk_gt_i32 s6, 0x207
	s_cselect_b64 s[4:5], -1, 0
	s_and_b64 vcc, exec, s[4:5]
	s_cbranch_vccnz .LBB0_519
	s_lshl_b32 s2, s6, 5
	s_and_b32 s2, s2, 0xffffff80
	s_and_b32 s9, s6, 3
	s_ashr_i32 s3, s2, 31
	s_lshl_b32 s12, s9, 8
	s_lshl_b64 s[2:3], s[2:3], 1
	v_lshl_add_u64 v[24:25], v[82:83], 0, s[2:3]
	v_add_u32_e32 v34, s12, v90
	v_add_u32_e32 v36, s12, v91
	v_add_u32_e32 v44, s12, v92
	v_add_u32_e32 v46, s12, v93
	s_lshl_b32 s9, s9, 7
	v_mad_i64_i32 v[0:1], s[10:11], v34, s94, v[24:25]
	v_mad_i64_i32 v[4:5], s[10:11], v36, s94, v[24:25]
	v_mad_i64_i32 v[8:9], s[10:11], v44, s94, v[24:25]
	v_mad_i64_i32 v[12:13], s[10:11], v46, s94, v[24:25]
	v_add_u32_e32 v16, s12, v94
	v_add_u32_e32 v18, s12, v95
	v_add_u32_e32 v26, s12, v96
	v_add_u32_e32 v28, s12, v97
	v_lshl_add_u64 v[42:43], v[84:85], 0, s[2:3]
	v_subrev_u32_e32 v34, s9, v34
	v_subrev_u32_e32 v36, s9, v36
	v_subrev_u32_e32 v44, s9, v44
	v_subrev_u32_e32 v46, s9, v46
	v_mad_i64_i32 v[16:17], s[10:11], v16, s94, v[24:25]
	v_mad_i64_i32 v[20:21], s[10:11], v18, s94, v[24:25]
	v_mad_i64_i32 v[26:27], s[10:11], v26, s94, v[24:25]
	v_mad_i64_i32 v[28:29], s[10:11], v28, s94, v[24:25]
	v_mad_i64_i32 v[34:35], s[2:3], v34, s94, v[42:43]
	v_mad_i64_i32 v[38:39], s[2:3], v36, s94, v[42:43]
	v_mad_i64_i32 v[44:45], s[2:3], v44, s94, v[42:43]
	v_mad_i64_i32 v[46:47], s[2:3], v46, s94, v[42:43]
	global_load_dwordx4 v[0:3], v[0:1], off
	s_nop 0
	global_load_dwordx4 v[4:7], v[4:5], off
	s_nop 0
	global_load_dwordx4 v[8:11], v[8:9], off
	s_nop 0
	global_load_dwordx4 v[12:15], v[12:13], off
	s_nop 0
	global_load_dwordx4 v[16:19], v[16:17], off
	s_nop 0
	global_load_dwordx4 v[20:23], v[20:21], off
	s_nop 0
	global_load_dwordx4 v[24:27], v[26:27], off
	s_nop 0
	global_load_dwordx4 v[28:31], v[28:29], off
	s_nop 0
	global_load_dwordx4 v[34:37], v[34:35], off
	s_nop 0
	global_load_dwordx4 v[38:41], v[38:39], off
	s_nop 0
	global_load_dwordx4 v[42:45], v[44:45], off
	s_nop 0
	global_load_dwordx4 v[46:49], v[46:47], off

.LBB0_523:
	global_load_ushort v1, v33, s[64:65] offset:18
	s_movk_i32 s2, 0x100
	v_readlane_b32 s14, v252, 47
	v_readlane_b32 s15, v252, 48
	s_waitcnt vmcnt(0)
	v_readfirstlane_b32 s0, v1
	s_cmp_lg_u32 s0, 0
	s_cselect_b64 s[0:1], -1, 0
	s_cmp_lg_u64 s[0:1], 0
	s_waitcnt lgkmcnt(0)
	s_addc_u32 s4, s2, 0
	s_not_b32 s3, s7
	s_cmp_lg_u64 s[0:1], 0
	s_addc_u32 s5, s3, s2
	s_cmpk_lt_i32 s5, 0x104
	s_cbranch_scc0 .LBB0_535
	v_and_b32_e32 v162, 0x3f8, v0
	v_readlane_b32 s0, v253, 7
	v_lshlrev_b32_e32 v20, 2, v162
	v_readlane_b32 s1, v253, 8
	s_nop 4
	global_load_dwordx4 v[0:3], v20, s[0:1] offset:16
	global_load_dwordx4 v[4:7], v20, s[0:1]
	v_readlane_b32 s0, v253, 5
	v_readlane_b32 s1, v253, 6
	s_nop 4
	global_load_dwordx4 v[8:11], v20, s[0:1] offset:16
	global_load_dwordx4 v[12:15], v20, s[0:1]
	v_readlane_b32 s0, v253, 9
	v_readlane_b32 s1, v253, 10
	s_nop 4
	global_load_dwordx4 v[16:19], v20, s[0:1] offset:16
	s_nop 0
	global_load_dwordx4 v[20:23], v20, s[0:1]
	v_readlane_b32 s0, v252, 17
	v_ashrrev_i32_e32 v24, 3, v88
	v_lshlrev_b32_e32 v32, 1, v162
	v_readlane_b32 s1, v252, 18
	s_lshl_b32 s6, s4, 6
	v_and_b32_e32 v24, -16, v24
	v_lshl_add_u64 v[164:165], s[0:1], 0, v[32:33]
	s_add_i32 s0, s6, 0xffffffbf
	v_add_u32_e32 v24, s0, v24
	s_lshl_b32 s0, s7, 6
	v_subrev_u32_e32 v163, s0, v24
	s_branch .LBB0_526

.LBB0_592:
	s_mov_b32 s0, s91
	v_readlane_b32 s1, v251, 36
	s_waitcnt vmcnt(0)
	s_nop 0
	v_lshl_add_u32 v0, s1, 6, v220
	s_nop 0
	v_lshl_add_u32 v112, s0, 9, v0
	s_mov_b32 s0, 0x20000
	v_cmp_gt_i32_e32 vcc, s0, v112
	s_and_saveexec_b64 s[0:1], vcc
	s_cbranch_execz .LBB0_599
	s_movk_i32 s2, 0x100
	s_waitcnt lgkmcnt(0)
	s_lshl_b32 s6, s2, 9
	s_mov_b64 s[2:3], 0
	s_branch .LBB0_595

.LBB0_657:
	v_readlane_b32 s0, v251, 36
	s_mov_b32 s83, s91
	v_readlane_b32 s14, v252, 47
	s_waitcnt vmcnt(0)
	v_lshl_add_u32 v1, s0, 6, v220
	s_cmp_eq_u32 s32, 7
	s_cselect_b32 s0, -8, 8
	s_add_i32 s48, s83, s0
	s_cmp_gt_i32 s48, s32
	v_readlane_b32 s15, v252, 48
	s_cbranch_scc1 .LBB0_797
	v_ashrrev_i32_e32 v0, 2, v1
	v_bfi_b32 v115, -16, v0, v1
	v_add_u32_e32 v7, 1, v115
	v_cvt_f32_i32_e32 v152, v7
	v_sub_u32_e32 v7, 0x80, v115
	v_and_b32_e32 v8, 64, v220
	v_cvt_f32_i32_e32 v153, v7
	v_xor_b32_e32 v7, 16, v220
	v_add_u32_e32 v8, 64, v8
	v_cmp_lt_i32_e32 vcc, v7, v8
	v_and_b32_e32 v2, 15, v1
	v_bfe_u32 v3, v1, 4, 2
	v_cndmask_b32_e32 v7, v220, v7, vcc
	v_lshlrev_b32_e32 v154, 2, v7
	v_xor_b32_e32 v7, 32, v220
	v_lshlrev_b32_e32 v0, 3, v1
	v_cmp_lt_i32_e32 vcc, v7, v8
	v_ashrrev_i32_e32 v118, 4, v1
	v_add_u32_e32 v8, 0x200, v1
	v_add_u32_e32 v9, 0x400, v1
	v_add_u32_e32 v1, 0x600, v1
	v_lshlrev_b32_e32 v114, 3, v3
	v_lshlrev_b32_e32 v5, 4, v3
	v_lshlrev_b32_e32 v3, 2, v3
	v_ashrrev_i32_e32 v120, 4, v8
	v_ashrrev_i32_e32 v122, 4, v9
	v_ashrrev_i32_e32 v124, 4, v1
	v_mad_i64_i32 v[126:127], s[0:1], v118, s94, 0
	v_mad_i64_i32 v[128:129], s[0:1], v120, s94, 0
	v_mad_i64_i32 v[130:131], s[0:1], v122, s94, 0
	v_mad_i64_i32 v[132:133], s[0:1], v124, s94, 0
	v_mul_u32_u24_e32 v156, 0x110, v2
	v_sub_u32_e32 v2, v115, v3
	v_cmp_gt_i32_e64 s[0:1], 1, v2
	v_sub_u32_e32 v10, 0, v2
	v_cvt_f32_u32_e32 v158, v2
	v_writelane_b32 v254, s0, 27
	v_or_b32_e32 v2, 1, v3
	v_cvt_f32_u32_e32 v157, v10
	v_writelane_b32 v254, s1, 28
	v_cmp_eq_u32_e64 s[0:1], v115, v3
	v_sub_u32_e32 v10, v115, v2
	v_cvt_f32_u32_e32 v160, v10
	v_writelane_b32 v254, s0, 29
	v_and_b32_e32 v0, 0x78, v0
	v_lshlrev_b32_e32 v32, 1, v0
	v_writelane_b32 v254, s1, 30
	v_cmp_gt_i32_e64 s[0:1], 1, v10
	s_mov_b64 s[68:69], s[70:71]
	v_lshl_add_u64 v[116:117], s[70:71], 0, v[32:33]
	v_writelane_b32 v254, s0, 31
	s_movk_i32 s6, 0x110
	s_movk_i32 s49, 0x100
	v_writelane_b32 v254, s1, 32
	v_cmp_eq_u32_e64 s[0:1], v115, v2
	v_sub_u32_e32 v2, 0, v10
	v_cvt_f32_u32_e32 v159, v2
	v_or_b32_e32 v2, 2, v3
	v_writelane_b32 v254, s0, 33
	v_sub_u32_e32 v10, v115, v2
	v_cvt_f32_u32_e32 v162, v10
	v_writelane_b32 v254, s1, 34
	v_cmp_gt_i32_e64 s[0:1], 1, v10
	v_mul_lo_u32 v151, v115, s6
	v_cndmask_b32_e32 v7, v220, v7, vcc
	v_writelane_b32 v254, s0, 35
	v_add_u32_e32 v4, 0, v32
	v_add_u32_e32 v6, 0, v151
	v_writelane_b32 v254, s1, 36
	v_cmp_eq_u32_e64 s[0:1], v115, v2
	v_sub_u32_e32 v2, 0, v10
	v_cvt_f32_u32_e32 v161, v2
	v_or_b32_e32 v2, 3, v3
	v_writelane_b32 v254, s0, 37
	v_sub_u32_e32 v10, v115, v2
	v_cvt_f32_u32_e32 v164, v10
	v_writelane_b32 v254, s1, 38
	v_cmp_gt_i32_e64 s[0:1], 1, v10
	v_lshlrev_b32_e32 v155, 2, v7
	v_mul_lo_u32 v7, v118, s6
	v_writelane_b32 v254, s0, 39
	v_mul_lo_u32 v8, v120, s6
	v_mul_lo_u32 v9, v122, s6
	v_writelane_b32 v254, s1, 40
	v_cmp_eq_u32_e64 s[0:1], v115, v2
	v_sub_u32_e32 v2, 0, v10
	v_cvt_f32_u32_e32 v163, v2
	v_or_b32_e32 v2, 16, v3
	v_writelane_b32 v254, s0, 41
	v_sub_u32_e32 v10, v115, v2
	v_cmp_gt_i32_e64 s[16:17], 1, v10
	v_writelane_b32 v254, s1, 42
	v_cmp_eq_u32_e64 s[0:1], v115, v2
	v_sub_u32_e32 v2, 0, v10
	v_cvt_f32_u32_e32 v165, v2
	v_or_b32_e32 v2, 17, v3
	v_writelane_b32 v254, s0, 43
	v_cvt_f32_u32_e32 v166, v10
	v_sub_u32_e32 v10, v115, v2
	v_writelane_b32 v254, s1, 44
	v_cmp_eq_u32_e64 s[0:1], v115, v2
	v_sub_u32_e32 v2, 0, v10
	v_cvt_f32_u32_e32 v167, v2
	v_or_b32_e32 v2, 18, v3
	v_cmp_gt_i32_e64 s[20:21], 1, v10
	v_writelane_b32 v254, s0, 45
	v_cvt_f32_u32_e32 v168, v10
	v_sub_u32_e32 v10, v115, v2
	v_writelane_b32 v254, s1, 46
	v_cmp_eq_u32_e64 s[0:1], v115, v2
	v_sub_u32_e32 v2, 0, v10
	v_cvt_f32_u32_e32 v169, v2
	v_or_b32_e32 v2, 19, v3
	v_cmp_gt_i32_e64 s[24:25], 1, v10
	v_writelane_b32 v254, s0, 47
	v_cvt_f32_u32_e32 v170, v10
	v_sub_u32_e32 v10, v115, v2
	v_writelane_b32 v254, s1, 48
	v_cmp_eq_u32_e64 s[0:1], v115, v2
	v_sub_u32_e32 v2, 0, v10
	v_cvt_f32_u32_e32 v171, v2
	v_or_b32_e32 v2, 32, v3
	v_cmp_gt_i32_e64 s[28:29], 1, v10
	v_writelane_b32 v254, s0, 49
	v_cvt_f32_u32_e32 v172, v10
	v_sub_u32_e32 v10, v115, v2
	v_writelane_b32 v254, s1, 50
	v_cmp_eq_u32_e64 s[0:1], v115, v2
	v_sub_u32_e32 v2, 0, v10
	v_cvt_f32_u32_e32 v173, v2
	v_or_b32_e32 v2, 33, v3
	v_cmp_gt_i32_e64 s[34:35], 1, v10
	v_writelane_b32 v254, s0, 51
	v_cvt_f32_u32_e32 v174, v10
	v_sub_u32_e32 v10, v115, v2
	v_writelane_b32 v254, s1, 52
	v_cmp_eq_u32_e64 s[0:1], v115, v2
	v_sub_u32_e32 v2, 0, v10
	v_cvt_f32_u32_e32 v175, v2
	v_or_b32_e32 v2, 34, v3
	v_cmp_gt_i32_e64 s[38:39], 1, v10
	v_writelane_b32 v254, s0, 53
	v_cvt_f32_u32_e32 v176, v10
	v_sub_u32_e32 v10, v115, v2
	v_writelane_b32 v254, s1, 54
	v_cmp_eq_u32_e64 s[0:1], v115, v2
	v_sub_u32_e32 v2, 0, v10
	v_cvt_f32_u32_e32 v177, v2
	v_or_b32_e32 v2, 35, v3
	v_cmp_gt_i32_e64 s[42:43], 1, v10
	v_writelane_b32 v254, s0, 55
	v_cvt_f32_u32_e32 v178, v10
	v_sub_u32_e32 v10, v115, v2
	v_writelane_b32 v254, s1, 56
	v_cmp_eq_u32_e64 s[0:1], v115, v2
	v_sub_u32_e32 v2, 0, v10
	v_cvt_f32_u32_e32 v179, v2
	v_or_b32_e32 v2, 48, v3
	v_cmp_gt_i32_e64 s[46:47], 1, v10
	v_writelane_b32 v254, s0, 57
	v_cvt_f32_u32_e32 v180, v10
	v_sub_u32_e32 v10, v115, v2
	v_writelane_b32 v254, s1, 58
	v_cmp_eq_u32_e64 s[0:1], v115, v2
	v_sub_u32_e32 v2, 0, v10
	v_cvt_f32_u32_e32 v181, v2
	v_or_b32_e32 v2, 49, v3
	v_cmp_gt_i32_e64 s[50:51], 1, v10
	v_writelane_b32 v254, s0, 59
	v_cvt_f32_u32_e32 v182, v10
	v_sub_u32_e32 v10, v115, v2
	v_writelane_b32 v254, s1, 60
	v_cmp_eq_u32_e64 s[0:1], v115, v2
	v_sub_u32_e32 v2, 0, v10
	v_cvt_f32_u32_e32 v183, v2
	v_or_b32_e32 v2, 50, v3
	v_cmp_gt_i32_e64 s[12:13], 1, v10
	v_writelane_b32 v254, s0, 61
	v_cvt_f32_u32_e32 v184, v10
	v_sub_u32_e32 v10, v115, v2
	v_writelane_b32 v254, s1, 62
	v_cmp_eq_u32_e64 s[0:1], v115, v2
	v_sub_u32_e32 v2, 0, v10
	v_cvt_f32_u32_e32 v185, v2
	v_or_b32_e32 v2, 51, v3
	v_cmp_gt_i32_e64 s[70:71], 1, v10
	v_cvt_f32_u32_e32 v186, v10
	v_sub_u32_e32 v10, v115, v2
	v_cmp_eq_u32_e64 s[2:3], v115, v2
	v_sub_u32_e32 v2, 0, v10
	v_writelane_b32 v254, s0, 63
	v_cvt_f32_u32_e32 v187, v2
	v_or_b32_e32 v2, 64, v3
	v_writelane_b32 v255, s1, 0
	v_cmp_gt_i32_e64 s[0:1], 1, v10
	v_writelane_b32 v255, s2, 1
	v_cvt_f32_u32_e32 v188, v10
	v_sub_u32_e32 v10, v115, v2
	v_writelane_b32 v255, s3, 2
	v_cmp_eq_u32_e64 s[2:3], v115, v2
	v_sub_u32_e32 v2, 0, v10
	v_cvt_f32_u32_e32 v189, v2
	v_or_b32_e32 v2, 0x41, v3
	v_cmp_gt_i32_e64 s[72:73], 1, v10
	v_writelane_b32 v255, s2, 3
	v_cvt_f32_u32_e32 v190, v10
	v_sub_u32_e32 v10, v115, v2
	v_writelane_b32 v255, s3, 4
	v_cmp_eq_u32_e64 s[2:3], v115, v2
	v_sub_u32_e32 v2, 0, v10
	v_cvt_f32_u32_e32 v191, v2
	v_or_b32_e32 v2, 0x42, v3
	v_cmp_gt_i32_e64 s[76:77], 1, v10
	v_writelane_b32 v255, s2, 5
	v_cvt_f32_u32_e32 v192, v10
	v_sub_u32_e32 v10, v115, v2
	v_writelane_b32 v255, s3, 6
	v_cmp_eq_u32_e64 s[2:3], v115, v2
	v_sub_u32_e32 v2, 0, v10
	v_cvt_f32_u32_e32 v193, v2
	v_or_b32_e32 v2, 0x43, v3
	v_cmp_gt_i32_e64 s[74:75], 1, v10
	v_writelane_b32 v255, s2, 7
	v_cvt_f32_u32_e32 v194, v10
	v_sub_u32_e32 v10, v115, v2
	v_writelane_b32 v255, s3, 8
	v_cmp_eq_u32_e64 s[2:3], v115, v2
	v_sub_u32_e32 v2, 0, v10
	v_cvt_f32_u32_e32 v195, v2
	v_or_b32_e32 v2, 0x50, v3
	v_cmp_gt_i32_e64 s[78:79], 1, v10
	v_writelane_b32 v255, s2, 9
	v_cvt_f32_u32_e32 v196, v10
	v_sub_u32_e32 v10, v115, v2
	v_writelane_b32 v255, s3, 10
	v_cmp_eq_u32_e64 s[2:3], v115, v2
	v_sub_u32_e32 v2, 0, v10
	v_cvt_f32_u32_e32 v197, v2
	v_or_b32_e32 v2, 0x51, v3
	v_cmp_gt_i32_e64 s[40:41], 1, v10
	v_writelane_b32 v255, s2, 11
	v_cvt_f32_u32_e32 v198, v10
	v_sub_u32_e32 v10, v115, v2
	v_writelane_b32 v255, s3, 12
	v_cmp_eq_u32_e64 s[2:3], v115, v2
	v_sub_u32_e32 v2, 0, v10
	v_cvt_f32_u32_e32 v199, v2
	v_or_b32_e32 v2, 0x52, v3
	v_cmp_gt_i32_e64 s[86:87], 1, v10
	v_writelane_b32 v255, s2, 13
	v_cvt_f32_u32_e32 v200, v10
	v_sub_u32_e32 v10, v115, v2
	v_writelane_b32 v255, s3, 14
	v_cmp_eq_u32_e64 s[2:3], v115, v2
	v_sub_u32_e32 v2, 0, v10
	v_cvt_f32_u32_e32 v201, v2
	v_or_b32_e32 v2, 0x53, v3
	v_cmp_gt_i32_e64 s[90:91], 1, v10
	v_writelane_b32 v255, s2, 15
	v_cvt_f32_u32_e32 v202, v10
	v_sub_u32_e32 v10, v115, v2
	v_writelane_b32 v255, s3, 16
	v_cmp_eq_u32_e64 s[2:3], v115, v2
	v_sub_u32_e32 v2, 0, v10
	v_cvt_f32_u32_e32 v203, v2
	v_or_b32_e32 v2, 0x60, v3
	v_cmp_gt_i32_e64 s[94:95], 1, v10
	v_cvt_f32_u32_e32 v204, v10
	v_sub_u32_e32 v10, v115, v2
	v_writelane_b32 v255, s2, 17
	v_cmp_eq_u32_e64 s[4:5], v115, v2
	v_sub_u32_e32 v2, 0, v10
	v_writelane_b32 v255, s3, 18
	v_cvt_f32_u32_e32 v205, v2
	v_or_b32_e32 v2, 0x61, v3
	v_cmp_gt_i32_e64 s[2:3], 1, v10
	v_writelane_b32 v255, s4, 19
	v_cvt_f32_u32_e32 v206, v10
	v_sub_u32_e32 v10, v115, v2
	v_writelane_b32 v255, s5, 20
	v_cmp_eq_u32_e64 s[4:5], v115, v2
	v_sub_u32_e32 v2, 0, v10
	v_cvt_f32_u32_e32 v207, v2
	v_or_b32_e32 v2, 0x62, v3
	v_cmp_gt_i32_e64 s[10:11], 1, v10
	v_writelane_b32 v255, s4, 21
	v_cvt_f32_u32_e32 v208, v10
	v_sub_u32_e32 v10, v115, v2
	v_writelane_b32 v255, s5, 22
	v_cmp_eq_u32_e64 s[4:5], v115, v2
	v_sub_u32_e32 v2, 0, v10
	v_cvt_f32_u32_e32 v209, v2
	v_or_b32_e32 v2, 0x63, v3
	v_cmp_gt_i32_e64 s[18:19], 1, v10
	v_writelane_b32 v255, s4, 23
	v_cvt_f32_u32_e32 v210, v10
	v_sub_u32_e32 v10, v115, v2
	v_writelane_b32 v255, s5, 24
	v_cmp_eq_u32_e64 s[4:5], v115, v2
	v_sub_u32_e32 v2, 0, v10
	v_cvt_f32_u32_e32 v211, v2
	v_or_b32_e32 v2, 0x70, v3
	s_waitcnt lgkmcnt(0)
	v_cmp_gt_i32_e64 s[26:27], 1, v10
	v_writelane_b32 v255, s4, 25
	v_cvt_f32_u32_e32 v212, v10
	v_sub_u32_e32 v10, v115, v2
	v_writelane_b32 v255, s5, 26
	v_cmp_eq_u32_e64 s[4:5], v115, v2
	v_sub_u32_e32 v2, 0, v10
	v_cvt_f32_u32_e32 v213, v2
	v_or_b32_e32 v2, 0x71, v3
	v_cmp_gt_i32_e64 s[36:37], 1, v10
	v_writelane_b32 v255, s4, 27
	v_cvt_f32_u32_e32 v214, v10
	v_sub_u32_e32 v10, v115, v2
	v_writelane_b32 v255, s5, 28
	v_cmp_eq_u32_e64 s[4:5], v115, v2
	v_sub_u32_e32 v2, 0, v10
	v_cvt_f32_u32_e32 v215, v2
	v_or_b32_e32 v2, 0x72, v3
	v_cmp_gt_i32_e64 s[44:45], 1, v10
	v_cvt_f32_u32_e32 v216, v10
	v_sub_u32_e32 v10, v115, v2
	v_cmp_eq_u32_e64 s[8:9], v115, v2
	v_sub_u32_e32 v2, 0, v10
	v_writelane_b32 v255, s4, 29
	v_cvt_f32_u32_e32 v217, v2
	v_or_b32_e32 v2, 0x73, v3
	v_writelane_b32 v255, s5, 30
	v_sub_u32_e32 v3, v115, v2
	v_writelane_b32 v255, s8, 31
	v_cmp_eq_u32_e64 s[14:15], v115, v2
	v_sub_u32_e32 v2, 0, v3
	v_writelane_b32 v255, s9, 32
	v_cmp_gt_i32_e64 s[8:9], 1, v3
	v_cvt_f32_u32_e32 v219, v2
	v_cvt_f32_u32_e32 v229, v3
	v_lshlrev_b32_e32 v2, 2, v118
	v_lshrrev_b32_e32 v3, 1, v118
	v_cmp_gt_i32_e64 s[4:5], 1, v10
	v_cvt_f32_u32_e32 v218, v10
	v_and_b32_e32 v2, 16, v2
	v_and_b32_e32 v3, 12, v3
	v_and_b32_e32 v10, 0xfffffe3, v118
	v_or3_b32 v2, v3, v10, v2
	v_mul_lo_u32 v231, v2, s6
	v_lshlrev_b32_e32 v2, 2, v120
	v_lshrrev_b32_e32 v3, 1, v120
	v_and_b32_e32 v2, 16, v2
	v_and_b32_e32 v3, 12, v3
	v_and_b32_e32 v10, 0xfffffe3, v120
	v_or3_b32 v2, v3, v10, v2
	v_mul_lo_u32 v232, v2, s6
	v_lshlrev_b32_e32 v2, 2, v122
	v_lshrrev_b32_e32 v3, 1, v122
	v_and_b32_e32 v2, 16, v2
	v_and_b32_e32 v3, 12, v3
	v_and_b32_e32 v10, 0xfffffe3, v122
	v_or3_b32 v2, v3, v10, v2
	v_mul_lo_u32 v233, v2, s6
	v_lshlrev_b32_e32 v2, 2, v124
	v_lshrrev_b32_e32 v3, 1, v124
	v_and_b32_e32 v2, 16, v2
	v_and_b32_e32 v3, 12, v3
	v_and_b32_e32 v10, 0xfffffe3, v124
	v_or3_b32 v2, v3, v10, v2
	v_mul_lo_u32 v1, v124, s6
	v_ashrrev_i32_e32 v119, 31, v118
	v_ashrrev_i32_e32 v121, 31, v120
	v_ashrrev_i32_e32 v123, 31, v122
	v_ashrrev_i32_e32 v125, 31, v124
	v_writelane_b32 v255, s14, 33
	v_mul_lo_u32 v234, v2, s6
	v_add_u32_e32 v2, s80, v5
	v_add_u32_e32 v3, s81, v5
	v_add_u32_e32 v150, 0, v5
	v_writelane_b32 v255, s15, 34
	v_add_u32_e32 v230, s80, v32
	v_add_u32_e32 v235, s81, v32
	v_lshl_add_u64 v[134:135], s[92:93], 0, v[32:33]
	v_lshlrev_b64 v[136:137], 8, v[118:119]
	v_lshlrev_b64 v[138:139], 8, v[120:121]
	v_lshlrev_b64 v[140:141], 8, v[122:123]
	v_lshlrev_b64 v[142:143], 8, v[124:125]
	v_add_u32_e32 v119, v4, v7
	v_add_u32_e32 v121, v4, v8
	v_add_u32_e32 v123, v4, v9
	v_add_u32_e32 v125, v4, v1
	v_lshlrev_b32_e32 v32, 1, v0
	v_add_u32_e32 v236, v6, v114
	v_add_u32_e32 v237, v2, v156
	v_add_u32_e32 v238, v3, v156
	s_branch .LBB0_660

.Lretctx_resume:
	v_readlane_b32 s0, v253, 17
	v_readlane_b32 s1, v253, 18
	s_andn2_b64 vcc, exec, s[0:1]
	s_cbranch_vccnz .LBB0_924
	s_movk_i32 s0, 0x100
	v_readlane_b32 s1, v251, 36
	s_mov_b32 s2, s91
	s_waitcnt lgkmcnt(0)
	s_cmp_gt_u32 s0, 16
	s_waitcnt vmcnt(0)
	v_lshl_add_u32 v0, s1, 6, v220
	s_cselect_b32 s1, 8, 0
	s_cmp_lt_i32 s2, s1
	s_cbranch_scc1 .LBB0_923

.LBB0_924:
	v_readlane_b32 s0, v251, 36
	s_mov_b32 s27, s91
	s_waitcnt vmcnt(0)
	v_lshl_add_u32 v0, s0, 6, v220
	s_waitcnt lgkmcnt(0)
	s_movk_i32 s26, 0x100
	s_cmpk_gt_i32 s27, 0xff
	v_readfirstlane_b32 s28, v0
	s_cbranch_scc1 .LBB0_950
	s_ashr_i32 s0, s27, 31
	s_lshr_b32 s0, s0, 29
	s_add_i32 s3, s27, s0
	s_and_b32 s0, s3, -8
	s_sub_i32 s4, s27, s0
	s_cmp_gt_i32 s4, -1
	s_mov_b64 s[0:1], -1
	s_cbranch_scc0 .LBB0_927
	s_lshl_b32 s2, s4, 5
	s_mov_b64 s[0:1], 0

.LBB0_1105:
	s_movk_i32 s0, 0x100
	s_add_i32 s36, s36, 1
	s_mov_b32 s5, 16
	s_mov_b64 s[18:19], s[20:21]
	s_mov_b64 s[16:17], s[14:15]
	s_waitcnt lgkmcnt(0)
	s_mul_i32 s22, s36, s0
	s_add_i32 s22, s22, s26
	v_readlane_b32 s0, v255, 50
	s_cmp_ge_i32 s22, s0
	s_cselect_b64 s[0:1], -1, 0
	s_and_b64 vcc, exec, s[0:1]
	s_cbranch_vccnz .LBB0_1116
	s_cmpk_lt_i32 s22, 0x100
	s_mov_b64 s[6:7], -1
	s_cbranch_scc0 .LBB0_1112
	s_ashr_i32 s2, s22, 31
	s_lshr_b32 s2, s2, 29
	s_add_i32 s4, s22, s2
	s_and_b32 s2, s4, -8
	s_sub_i32 s5, s22, s2
	s_cmp_gt_i32 s5, -1
	s_mov_b64 s[2:3], -1
	s_cbranch_scc0 .LBB0_1109
	s_lshl_b32 s6, s5, 5
	s_mov_b64 s[2:3], 0

.LBB0_1183:
	s_or_b64 exec, exec, s[0:1]
	s_movk_i32 s0, 0x4100
	v_cmp_gt_i32_e32 vcc, s0, v112
	s_and_saveexec_b64 s[4:5], vcc
	s_cbranch_execz .LBB0_1202
	s_waitcnt vmcnt(0)
	v_pk_add_f32 v[46:47], v[46:47], 1.0 op_sel_hi:[1,0]
	v_readlane_b32 s0, v254, 15
	v_pk_mul_f32 v[70:71], v[20:21], v[46:47]
	v_pk_add_f32 v[20:21], v[44:45], 1.0 op_sel_hi:[1,0]
	v_mov_b32_e32 v59, v33
	v_pk_mul_f32 v[72:73], v[40:41], v[20:21]
	v_pk_add_f32 v[20:21], v[34:35], 1.0 op_sel_hi:[1,0]
	v_readlane_b32 s1, v254, 16
	v_pk_mul_f32 v[78:79], v[16:17], v[20:21]
	v_and_b32_e32 v16, 64, v220
	v_add_u32_e32 v16, 64, v16
	v_xor_b32_e32 v17, 1, v220
	v_cmp_lt_i32_e32 vcc, v17, v16
	v_mov_b32_e32 v89, v33
	v_lshl_add_u64 v[60:61], s[0:1], 0, v[58:59]
	v_cndmask_b32_e32 v17, v220, v17, vcc
	v_lshlrev_b32_e32 v116, 2, v17
	v_xor_b32_e32 v17, 2, v220
	v_cmp_lt_i32_e32 vcc, v17, v16
	v_lshl_add_u64 v[62:63], s[0:1], 0, v[88:89]
	s_movk_i32 s0, 0x100
	v_cndmask_b32_e32 v17, v220, v17, vcc
	v_lshlrev_b32_e32 v117, 2, v17
	v_xor_b32_e32 v17, 4, v220
	v_cmp_lt_i32_e32 vcc, v17, v16
	s_waitcnt lgkmcnt(0)
	s_lshl_b32 s6, s0, 3
	v_readlane_b32 s0, v252, 9
	v_cndmask_b32_e32 v17, v220, v17, vcc
	v_lshlrev_b32_e32 v118, 2, v17
	v_xor_b32_e32 v17, 8, v220
	v_cmp_lt_i32_e32 vcc, v17, v16
	v_pk_add_f32 v[48:49], v[48:49], 1.0 op_sel_hi:[1,0]
	v_readlane_b32 s1, v252, 10
	v_cndmask_b32_e32 v17, v220, v17, vcc
	v_lshlrev_b32_e32 v119, 2, v17
	v_xor_b32_e32 v17, 16, v220
	v_cmp_lt_i32_e32 vcc, v17, v16
	v_pk_mul_f32 v[68:69], v[22:23], v[48:49]
	v_pk_add_f32 v[22:23], v[42:43], 1.0 op_sel_hi:[1,0]
	v_cndmask_b32_e32 v17, v220, v17, vcc
	v_lshlrev_b32_e32 v120, 2, v17
	v_xor_b32_e32 v17, 32, v220
	v_cmp_lt_i32_e32 vcc, v17, v16
	v_lshl_add_u64 v[80:81], s[0:1], 0, v[32:33]
	v_readlane_b32 s2, v254, 23
	v_readlane_b32 s0, v254, 21
	v_pk_mul_f32 v[74:75], v[38:39], v[22:23]
	v_pk_add_f32 v[22:23], v[36:37], 1.0 op_sel_hi:[1,0]
	v_cndmask_b32_e32 v16, v220, v17, vcc
	v_readlane_b32 s3, v254, 24
	v_readlane_b32 s1, v254, 22
	v_pk_mul_f32 v[76:77], v[18:19], v[22:23]
	v_lshlrev_b32_e32 v121, 2, v16
	v_lshl_add_u64 v[84:85], s[0:1], 0, v[58:59]
	v_lshl_add_u64 v[86:87], s[2:3], 0, v[88:89]
	v_lshl_add_u64 v[88:89], s[0:1], 0, v[88:89]
	v_lshlrev_b64 v[16:17], 12, v[112:113]
	v_and_b32_e32 v18, 63, v90
	v_readlane_b32 s0, v252, 11
	v_lshl_or_b32 v16, v18, 5, v16
	v_readlane_b32 s1, v252, 12
	v_pk_add_f32 v[56:57], v[56:57], 1.0 op_sel_hi:[1,0]
	v_pk_add_f32 v[54:55], v[54:55], 1.0 op_sel_hi:[1,0]
	s_ashr_i32 s7, s6, 31
	v_lshl_add_u64 v[90:91], s[0:1], 0, v[16:17]
	v_mov_b64_e32 v[16:17], v[28:29]
	v_mov_b64_e32 v[20:21], v[24:25]
	v_pk_mul_f32 v[64:65], v[52:53], v[56:57]
	v_pk_mul_f32 v[66:67], v[50:51], v[54:55]
	s_lshl_b64 s[8:9], s[6:7], 11
	v_lshl_add_u64 v[82:83], s[2:3], 0, v[58:59]
	s_lshl_b64 s[10:11], s[6:7], 12
	s_mov_b64 s[12:13], 0
	v_mov_b64_e32 v[18:19], v[30:31]
	v_mov_b64_e32 v[22:23], v[26:27]
	s_branch .LBB0_1186

.LBB0_1210:
	v_readlane_b32 s0, v251, 45
	v_readlane_b32 s1, v251, 46
	global_load_dword v15, v33, s[56:57] sc1
	global_load_dword v14, v33, s[58:59] sc1
	global_load_dword v13, v33, s[60:61] sc1
	s_waitcnt vmcnt(2)
	v_readfirstlane_b32 s87, v15
	global_load_dword v12, v33, s[0:1] sc1
	v_readlane_b32 s0, v251, 47
	v_readlane_b32 s1, v251, 48
	s_waitcnt vmcnt(2)
	v_add_u32_e32 v15, v14, v15
	s_waitcnt vmcnt(1)
	v_add_u32_e32 v15, v15, v13
	s_waitcnt vmcnt(0)
	v_add_u32_e32 v15, v15, v12
	global_load_dword v11, v33, s[0:1] sc1
	v_readlane_b32 s0, v251, 49
	v_readlane_b32 s1, v251, 50
	s_waitcnt vmcnt(0)
	v_add_u32_e32 v15, v15, v11
	s_nop 2
	global_load_dword v10, v33, s[0:1] sc1
	v_readlane_b32 s0, v251, 51
	v_readlane_b32 s1, v251, 52
	s_waitcnt vmcnt(0)
	v_add_u32_e32 v15, v15, v10
	s_nop 2
	global_load_dword v9, v33, s[0:1] sc1
	v_readlane_b32 s0, v251, 53
	v_readlane_b32 s1, v251, 54
	s_waitcnt vmcnt(0)
	v_add_u32_e32 v15, v15, v9
	s_nop 2
	global_load_dword v8, v33, s[0:1] sc1
	v_readlane_b32 s0, v251, 55
	v_readlane_b32 s1, v251, 56
	s_waitcnt vmcnt(0)
	v_add_u32_e32 v15, v15, v8
	s_nop 2
	global_load_dword v7, v33, s[0:1] sc1
	v_readlane_b32 s0, v251, 57
	v_readlane_b32 s1, v251, 58
	s_waitcnt vmcnt(0)
	v_add_u32_e32 v15, v15, v7
	s_nop 2
	global_load_dword v6, v33, s[0:1] sc1
	v_readlane_b32 s0, v251, 59
	v_readlane_b32 s1, v251, 60
	s_waitcnt vmcnt(0)
	v_add_u32_e32 v15, v15, v6
	s_nop 2
	global_load_dword v5, v33, s[0:1] sc1
	v_readlane_b32 s0, v251, 61
	v_readlane_b32 s1, v251, 62
	s_waitcnt vmcnt(0)
	v_add_u32_e32 v15, v15, v5
	s_nop 2
	global_load_dword v4, v33, s[0:1] sc1
	v_readlane_b32 s0, v251, 63
	v_readlane_b32 s1, v252, 0
	s_waitcnt vmcnt(0)
	v_add_u32_e32 v15, v15, v4
	s_nop 2
	global_load_dword v3, v33, s[0:1] sc1
	v_readlane_b32 s0, v252, 1
	v_readlane_b32 s1, v252, 2
	s_waitcnt vmcnt(0)
	v_add_u32_e32 v15, v15, v3
	s_nop 2
	global_load_dword v2, v33, s[0:1] sc1
	v_readlane_b32 s0, v252, 3
	v_readlane_b32 s1, v252, 4
	s_waitcnt vmcnt(0)
	v_add_u32_e32 v15, v15, v2
	s_nop 2
	global_load_dword v1, v33, s[0:1] sc1
	v_readlane_b32 s0, v252, 5
	v_readlane_b32 s1, v252, 6
	s_waitcnt vmcnt(0)
	v_add_u32_e32 v15, v15, v1
	s_waitcnt lgkmcnt(0)
	s_nop 1
	global_load_dword v0, v33, s[0:1] sc1
	s_movk_i32 s2, 0x100
	s_mov_b64 s[0:1], -1
	s_waitcnt vmcnt(0)
	v_add_u32_e32 v15, v15, v0
	s_waitcnt lgkmcnt(0)
	v_cmp_eq_u32_e32 vcc, s2, v15
	s_mov_b64 s[2:3], -1
	s_cbranch_vccnz .LBB0_1209
	s_and_b32 s0, s6, 0xff
	s_cmp_eq_u32 s0, 0
	s_mov_b64 s[0:1], -1
	s_mov_b64 s[4:5], -1
	s_sleep 1
	s_cbranch_scc1 .LBB0_1214
	s_and_b64 vcc, exec, s[4:5]
	s_cbranch_vccz .LBB0_1209

.LBB0_1269:
	s_movk_i32 s0, 0x100
	s_add_i32 s34, s34, 1
	s_mov_b64 s[10:11], s[14:15]
	s_mov_b64 s[12:13], s[16:17]
	s_waitcnt lgkmcnt(0)
	s_mul_i32 s3, s34, s0
	s_add_i32 s3, s3, s91
	s_and_b32 s0, s91, 63
	s_cmp_lg_u32 s0, 0
	s_cbranch_scc1 .Lupr1_done
	s_cmp_gt_u32 s34, 5
	s_cbranch_scc1 .Lupr1_done
	s_cmpk_gt_i32 s3, 0x595
	s_cbranch_scc1 .Lupr1_done
	s_add_i32 s3, s91, s34

.LBB0_1353:
	s_movk_i32 s0, 0x100
	s_add_i32 s28, s28, 1
	s_mov_b32 s38, 44
	s_mov_b64 s[8:9], s[12:13]
	s_mov_b64 s[6:7], s[10:11]
	s_waitcnt lgkmcnt(0)
	s_mul_i32 s14, s28, s0
	s_add_i32 s14, s14, s18
	s_cmp_ge_i32 s14, s20
	s_cselect_b64 s[0:1], -1, 0
	s_and_b64 vcc, exec, s[0:1]
	s_cbranch_vccnz .LBB0_1364
	s_cmpk_lt_i32 s14, 0x100
	s_mov_b64 s[2:3], -1
	s_cbranch_scc0 .LBB0_1360
	s_ashr_i32 s2, s14, 31
	s_lshr_b32 s2, s2, 29
	s_add_i32 s4, s14, s2
	s_and_b32 s2, s4, -8
	s_sub_i32 s5, s14, s2
	s_cmp_gt_i32 s5, -1
	s_mov_b64 s[2:3], -1
	s_cbranch_scc0 .LBB0_1357
	s_lshl_b32 s6, s5, 5
	s_mov_b64 s[2:3], 0

.LBB0_1373:
	v_readlane_b32 s4, v252, 47
	v_readlane_b32 s5, v252, 48
	s_cmp_ge_i32 s86, s4
	s_cselect_b64 s[0:1], -1, 0
	s_cmp_lt_i32 s86, s5
	s_cselect_b64 s[2:3], -1, 0
	s_and_b64 s[0:1], s[0:1], s[2:3]
	s_and_b64 vcc, exec, s[0:1]
	s_cbranch_vccz .LBB0_1436
	v_readlane_b32 s40, v252, 26
	s_cmp_le_i32 s86, s4
	v_readlane_b32 s42, v252, 28
	v_readlane_b32 s43, v252, 29
	v_readlane_b32 s44, v252, 30
	v_readlane_b32 s45, v252, 31
	v_readlane_b32 s46, v252, 32
	v_readlane_b32 s47, v252, 33
	v_readlane_b32 s41, v252, 27
	s_cbranch_scc1 .LBB0_1431
	s_waitcnt vmcnt(0)
	v_readlane_b32 s0, v251, 36
	s_waitcnt vmcnt(0) lgkmcnt(0)
	s_barrier
	s_nop 0
	v_lshl_add_u32 v0, s0, 6, v220
	s_nop 0
	v_cmp_eq_u32_e32 vcc, 0, v0
	s_and_saveexec_b64 s[30:31], vcc
	s_cbranch_execz .LBB0_1430
	s_add_i32 s1, 0, 0x23ff0
	v_mov_b32_e32 v0, s1
	s_waitcnt vmcnt(0) expcnt(0) lgkmcnt(0)
	s_getreg_b32 s0, hwreg(HW_REG_XCC_ID, 0, 4)
	ds_read_b32 v2, v0
	s_add_i32 s1, 0, 0x23ff4
	v_mov_b32_e32 v0, s1
	ds_read_b32 v0, v0
	s_and_b32 s33, s0, 15
	s_waitcnt lgkmcnt(1)
	v_cmp_ne_u32_e32 vcc, 0, v2
	s_cbranch_vccnz .LBB0_1394
	s_movk_i32 s6, 0x100
	s_mov_b32 s7, 1
	v_mov_b32_e32 v15, 0
	s_branch .LBB0_1379

.LBB0_1431:
	v_readlane_b32 s0, v251, 36
	s_movk_i32 s10, 0x4000
	s_waitcnt vmcnt(0)
	v_lshl_add_u32 v22, s0, 6, v220
	s_lshl_b32 s0, s91, 3
	v_ashrrev_i32_e32 v20, 6, v22
	v_add_u32_e32 v8, s0, v20
	v_cmp_gt_i32_e32 vcc, s10, v8
	s_and_saveexec_b64 s[2:3], vcc
	s_cbranch_execz .LBB0_1436
	v_add_u32_e32 v36, 0x100, v8
	v_lshlrev_b32_e32 v0, 3, v22
	v_ashrrev_i32_e32 v37, 31, v36
	v_and_b32_e32 v10, 0x1f8, v0
	v_lshlrev_b64 v[8:9], 11, v[36:37]
	v_lshl_add_u64 v[8:9], s[46:47], 0, v[8:9]
	v_lshlrev_b32_e32 v24, 1, v10
	v_mov_b32_e32 v25, 0
	v_lshlrev_b32_e32 v21, 2, v10
	v_lshl_add_u64 v[26:27], v[8:9], 0, v[24:25]
	global_load_dwordx4 v[0:3], v21, s[42:43] offset:16
	global_load_dwordx4 v[4:7], v21, s[42:43]
	global_load_dwordx4 v[28:31], v[26:27], off
	global_load_dwordx4 v[16:19], v[26:27], off offset:1024
	global_load_dwordx4 v[8:11], v21, s[42:43] offset:2064
	global_load_dwordx4 v[12:15], v21, s[42:43] offset:2048
	s_movk_i32 s1, 0x100
	v_and_b32_e32 v23, 64, v220
	v_xor_b32_e32 v26, 1, v220
	v_add_u32_e32 v23, 64, v23
	v_xor_b32_e32 v27, 2, v220
	s_waitcnt lgkmcnt(0)
	s_lshl_b32 s4, s1, 3
	s_ashr_i32 s5, s4, 31
	v_cmp_lt_i32_e32 vcc, v26, v23
	s_lshl_b64 s[6:7], s[4:5], 11
	v_xor_b32_e32 v32, 4, v220
	v_cndmask_b32_e32 v26, v220, v26, vcc
	v_cmp_lt_i32_e32 vcc, v27, v23
	s_add_u32 s12, s46, s6
	v_xor_b32_e32 v33, 8, v220
	v_ashrrev_i32_e32 v21, 31, v20
	v_cndmask_b32_e32 v27, v220, v27, vcc
	v_cmp_lt_i32_e32 vcc, v32, v23
	s_addc_u32 s13, s47, s7
	s_ashr_i32 s1, s0, 31
	v_xor_b32_e32 v34, 16, v220
	v_cndmask_b32_e32 v32, v220, v32, vcc
	v_cmp_lt_i32_e32 vcc, v33, v23
	v_lshl_add_u64 v[20:21], v[20:21], 0, s[0:1]
	v_xor_b32_e32 v35, 32, v220
	v_and_b32_e32 v22, 63, v22
	v_cndmask_b32_e32 v33, v220, v33, vcc
	v_cmp_lt_i32_e32 vcc, v34, v23
	v_lshlrev_b64 v[20:21], 12, v[20:21]
	v_lshl_or_b32 v20, v22, 5, v20
	v_cndmask_b32_e32 v34, v220, v34, vcc
	v_cmp_lt_i32_e32 vcc, v35, v23
	s_mov_b64 s[8:9], 0x810
	v_lshl_add_u64 v[20:21], s[44:45], 0, v[20:21]
	v_cndmask_b32_e32 v23, v220, v35, vcc
	v_lshlrev_b32_e32 v39, 2, v26
	v_lshlrev_b32_e32 v40, 2, v27
	v_lshlrev_b32_e32 v41, 2, v32
	v_lshlrev_b32_e32 v42, 2, v33
	v_lshlrev_b32_e32 v43, 2, v34
	v_lshlrev_b32_e32 v44, 2, v23
	v_lshl_add_u64 v[32:33], s[12:13], 0, v[24:25]
	v_lshl_add_u64 v[34:35], v[20:21], 0, s[8:9]
	s_mov_b64 s[2:3], 0
	s_movk_i32 s11, 0x3fff
	v_mov_b32_e32 v38, 0x358637bd
	s_lshl_b64 s[6:7], s[4:5], 12
	s_waitcnt vmcnt(3)
	v_mov_b64_e32 v[20:21], v[28:29]
	s_waitcnt vmcnt(2)
	v_mov_b64_e32 v[26:27], v[18:19]
	v_mov_b64_e32 v[22:23], v[30:31]
	v_mov_b64_e32 v[24:25], v[16:17]
	s_branch .LBB0_1434
